# speedup vs baseline: 1.0214x; 1.0033x over previous
; __device__ __forceinline__ void finishSM(f32x16& p0, f32x16& p1, float alpha, float& l_reg, bf16x8& pa0, bf16x8& pa1, bf16x8& pa2, bf16x8& pa3) {
; #pragma unroll
;   for (int r = 0; r < 16; ++r) p1[r] = __builtin_amdgcn_exp2f(p1[r]);
;   float ps = 0;
; #pragma unroll
;   for (int r = 0; r < 16; ++r) ps += p0[r];
; #pragma unroll
;   for (int r = 0; r < 16; ++r) ps += p1[r];
;   { auto rr = __builtin_amdgcn_permlane32_swap(__float_as_uint(ps), __float_as_uint(ps), false, false);
;     ps = __uint_as_float(rr[0]) + __uint_as_float(rr[1]); }
;   l_reg = l_reg * alpha + ps;
;     ...
;   PK4(p0, 0, pa0); PK4(p0, 8, pa1); PK4(p1, 0, pa2); PK4(p1, 8, pa3);
;     ...
; }
; template <int BUFOFF>
; __device__ __forceinline__ void qkt_mla(f32x16& p0, f32x16& p1, const int* ka, const bf16x8* qr, const char* qlds) {
;   typedef __attribute__((address_space(3))) const bf16x8* lp;
;   p0 = f32x16{}; p1 = f32x16{};
; #pragma unroll
;   for (int d0 = 0; d0 < 12; ++d0) {
;     const int a = ka[d0 & 3] + (d0 >> 2) * 128 + BUFOFF;
;     const bf16x8 b0 = *(lp)(a), b1 = *(lp)(a + 12288);
;     bf16x8 qf;
;     qf = qr[d0];
;     p0 = __builtin_amdgcn_mfma_f32_32x32x16_bf16(b0, qf, p0, 0, 0, 0);
;     p1 = __builtin_amdgcn_mfma_f32_32x32x16_bf16(b1, qf, p1, 0, 0, 0);
;   }
; }
.LBB0_115:
	s_mov_b32 s55, s43
	s_mov_b32 s43, s52
	ds_read_b128 v[64:67], v169 offset:24576
	ds_read_b128 v[68:71], v169 offset:36864
	ds_read_b128 v[214:217], v190 offset:24576
	ds_read_b128 v[218:221], v190 offset:36864
	s_waitcnt lgkmcnt(0)
	v_mfma_f32_32x32x16_bf16 v[80:95], v[64:67], v[140:143], v[226:241]
	v_add_f32_e32 v144, v200, v145
	v_mfma_f32_32x32x16_bf16 v[64:79], v[68:71], v[140:143], v[226:241]
	v_add_f32_e32 v243, v203, v210
	v_add_f32_e32 v244, v202, v208
	v_add_f32_e32 v245, v205, v212
	v_add_f32_e32 v246, v199, v211
	v_add_f32_e32 v247, v201, v213
	v_mfma_f32_32x32x16_bf16 v[80:95], v[214:217], v[136:139], v[80:95]
	v_add_f32_e32 v251, v204, v207
	v_add_f32_e32 v252, v206, v209
	v_mov_b32_e32 v196, v158
	v_add_f32_e32 v144, v172, v144
	v_add_f32_e32 v243, v173, v243
	v_mfma_f32_32x32x16_bf16 v[64:79], v[218:221], v[136:139], v[64:79]
	ds_read_b128 v[214:217], v193 offset:24576
	ds_read_b128 v[218:221], v193 offset:36864
	v_add_f32_e32 v244, v170, v244
	v_add_f32_e32 v245, v171, v245
	v_add_f32_e32 v246, v196, v246
	v_mov_b32_e32 v222, v147
	v_mov_b32_e32 v223, v154
	v_mov_b32_e32 v224, v155
	s_waitcnt lgkmcnt(0)
	v_mfma_f32_32x32x16_bf16 v[80:95], v[214:217], v[132:135], v[80:95]
	v_mfma_f32_32x32x16_bf16 v[64:79], v[218:221], v[132:135], v[64:79]
	ds_read_b128 v[214:217], v192 offset:24576
	ds_read_b128 v[218:221], v192 offset:36864
	s_waitcnt lgkmcnt(0)
	v_mfma_f32_32x32x16_bf16 v[80:95], v[214:217], v[128:131], v[80:95]
	v_mfma_f32_32x32x16_bf16 v[64:79], v[218:221], v[128:131], v[64:79]
	ds_read_b128 v[214:217], v169 offset:24704
	ds_read_b128 v[218:221], v169 offset:36992
	s_waitcnt lgkmcnt(0)
	v_mfma_f32_32x32x16_bf16 v[80:95], v[214:217], v[124:127], v[80:95]
	v_mfma_f32_32x32x16_bf16 v[64:79], v[218:221], v[124:127], v[64:79]
	ds_read_b128 v[214:217], v190 offset:24704
	ds_read_b128 v[218:221], v190 offset:36992
	s_waitcnt lgkmcnt(0)
	v_mfma_f32_32x32x16_bf16 v[80:95], v[214:217], v[120:123], v[80:95]
	v_mfma_f32_32x32x16_bf16 v[64:79], v[218:221], v[120:123], v[64:79]
	ds_read_b128 v[214:217], v193 offset:24704
	ds_read_b128 v[218:221], v193 offset:36992
	s_waitcnt lgkmcnt(0)
	v_mfma_f32_32x32x16_bf16 v[80:95], v[214:217], v[116:119], v[80:95]
	v_mfma_f32_32x32x16_bf16 v[64:79], v[218:221], v[116:119], v[64:79]
	ds_read_b128 v[214:217], v192 offset:24704
	ds_read_b128 v[218:221], v192 offset:36992
	s_waitcnt lgkmcnt(0)
	v_mfma_f32_32x32x16_bf16 v[80:95], v[214:217], v[112:115], v[80:95]
	v_mfma_f32_32x32x16_bf16 v[64:79], v[218:221], v[112:115], v[64:79]
	ds_read_b128 v[214:217], v169 offset:24832
	ds_read_b128 v[218:221], v169 offset:37120
	s_waitcnt lgkmcnt(0)
	v_mfma_f32_32x32x16_bf16 v[80:95], v[214:217], v[108:111], v[80:95]
	v_mfma_f32_32x32x16_bf16 v[64:79], v[218:221], v[108:111], v[64:79]
	ds_read_b128 v[214:217], v190 offset:24832
	ds_read_b128 v[218:221], v190 offset:37120
	s_waitcnt lgkmcnt(0)
	v_mfma_f32_32x32x16_bf16 v[80:95], v[214:217], v[104:107], v[80:95]
	v_mfma_f32_32x32x16_bf16 v[64:79], v[218:221], v[104:107], v[64:79]
	ds_read_b128 v[214:217], v193 offset:24832
	ds_read_b128 v[218:221], v193 offset:37120
	s_waitcnt lgkmcnt(0)
	v_mfma_f32_32x32x16_bf16 v[80:95], v[214:217], v[100:103], v[80:95]
	v_mfma_f32_32x32x16_bf16 v[64:79], v[218:221], v[100:103], v[64:79]
	ds_read_b128 v[214:217], v192 offset:24832
	ds_read_b128 v[218:221], v192 offset:37120
	s_waitcnt lgkmcnt(0)
	v_mfma_f32_32x32x16_bf16 v[80:95], v[214:217], v[96:99], v[80:95]
	v_mov_b32_e32 v214, v159
	v_mov_b32_e32 v215, v152
	v_mov_b32_e32 v216, v153
	v_mov_b32_e32 v217, v150
	v_add_f32_e32 v247, v214, v247
	v_add_f32_e32 v251, v215, v251
	v_add_f32_e32 v252, v216, v252
	v_mfma_f32_32x32x16_bf16 v[64:79], v[218:221], v[96:99], v[64:79]
	v_mov_b32_e32 v218, v151
	v_mov_b32_e32 v219, v148
	v_mov_b32_e32 v220, v149
	v_mov_b32_e32 v221, v146
	v_add_f32_e32 v144, v217, v144
	v_add_f32_e32 v243, v218, v243
	v_add_f32_e32 v244, v219, v244
	v_add_f32_e32 v245, v220, v245
	v_add_f32_e32 v246, v221, v246
	v_add_f32_e32 v247, v222, v247
	v_add_f32_e32 v251, v223, v251
	v_add_f32_e32 v252, v224, v252
	v_add_f32_e32 v144, v144, v243
	v_add_f32_e32 v244, v244, v245
	v_add_f32_e32 v246, v246, v247
	v_add_f32_e32 v251, v251, v252
	v_add_f32_e32 v144, v144, v244
	v_add_f32_e32 v246, v246, v251
	v_add_f32_e32 v158, v144, v246
	v_mov_b32_e32 v159, v158
	v_cvt_pk_bf16_f32 v144, v145, v210
	v_cvt_pk_bf16_f32 v145, v208, v212
	v_cvt_pk_bf16_f32 v146, v211, v213
	v_cvt_pk_bf16_f32 v147, v207, v209
	v_cvt_pk_bf16_f32 v148, v200, v203
	v_cvt_pk_bf16_f32 v149, v202, v205
	v_cvt_pk_bf16_f32 v150, v199, v201
	v_cvt_pk_bf16_f32 v151, v204, v206
	v_cvt_pk_bf16_f32 v152, v172, v173
	v_cvt_pk_bf16_f32 v153, v170, v171
	v_cvt_pk_bf16_f32 v154, v196, v214
	s_nop 1
	v_permlane32_swap_b32_e32 v158, v159
	v_cvt_pk_bf16_f32 v155, v215, v216
	v_cvt_pk_bf16_f32 v170, v217, v218
	v_cvt_pk_bf16_f32 v171, v219, v220
	v_cvt_pk_bf16_f32 v172, v221, v222
	v_cvt_pk_bf16_f32 v173, v223, v224
	v_readlane_b32 s58, v249, 37
	v_readlane_b32 s59, v249, 38
	s_add_u32 s56, s58, s47
	s_addc_u32 s57, s59, s50
	s_add_u32 s4, s56, 0x17060000
	s_addc_u32 s5, s57, 0
	s_add_u32 s58, s58, s14
	s_addc_u32 s59, s59, s15
	s_add_u32 s60, s58, 0x1a040000
	s_mov_b32 m0, s41
	s_addc_u32 s61, s59, 0
	s_lshl_b32 s52, s54, 14
	s_add_i32 s62, s40, s52
	global_load_lds_dwordx4 v188, s[4:5]
	s_mov_b32 m0, s42
	s_nop 0
	global_load_lds_dwordx4 v189, s[4:5]
	s_add_i32 m0, s41, 0x4000
	s_nop 0
	global_load_lds_dwordx4 v191, s[4:5]
	s_mov_b32 m0, s62
	s_nop 0
	global_load_lds_dwordx4 v194, s[60:61]
	s_add_i32 m0, s62, 0x2000
	s_nop 0
	global_load_lds_dwordx4 v195, s[60:61]
	s_lshl_b32 s60, s43, 14
	v_add_u32_e32 v196, s60, v167
	ds_read_b64_tr_b16 v[200:201], v196 offset:0
	ds_read_b64_tr_b16 v[202:203], v196 offset:0x800
	ds_read_b64_tr_b16 v[204:205], v196 offset:0x1000
	ds_read_b64_tr_b16 v[206:207], v196 offset:0x1800
	ds_read_b64_tr_b16 v[208:209], v196 offset:0x2000
	ds_read_b64_tr_b16 v[210:211], v196 offset:0x2800
	ds_read_b64_tr_b16 v[212:213], v196 offset:0x3000
	ds_read_b64_tr_b16 v[214:215], v196 offset:0x3800
	s_nop 0
	s_waitcnt lgkmcnt(6)
; #define SBAR() __builtin_amdgcn_sched_barrier(0)
; template <int MLA>
; __device__ __forceinline__ void partialSM(f32x16& p0, f32x16& p1, float& m_reg, float& mn, float& alpha) {
;     ...
;   float pmax = p0[0];
; #pragma unroll
;   for (int r = 1; r < 16; ++r) pmax = fmaxf(pmax, p0[r]);
; #pragma unroll
;   for (int r = 0; r < 16; ++r) pmax = fmaxf(pmax, p1[r]);
;   { auto rr = __builtin_amdgcn_permlane32_swap(__float_as_uint(pmax), __float_as_uint(pmax), false, false);
;     pmax = fmaxf(__uint_as_float(rr[0]), __uint_as_float(rr[1])); }
;   if (__builtin_expect(__all(pmax - m_reg <= THR / SCALE), 1)) { mn = m_reg; alpha = 1.f; }
;   else { mn = fmaxf(m_reg, pmax); alpha = __builtin_amdgcn_exp2f((m_reg - mn) * C); m_reg = mn; }
;   float mnC = -mn * C;
; #pragma unroll
;   for (int r = 0; r < 16; ++r) p0[r] = fmaf(p0[r], C, mnC);
; #pragma unroll
;   for (int r = 0; r < 16; ++r) p1[r] = fmaf(p1[r], C, mnC);
; #pragma unroll
;   for (int r = 0; r < 16; ++r) p0[r] = __builtin_amdgcn_exp2f(p0[r]);
; }
; template <int D0> __device__ __forceinline__ void pv_one_t(f32x16& od, int vb, bf16x8 pa0, bf16x8 pa1, bf16x8 pa2, bf16x8 pa3) {
;   const s16x4 l0 = tr_read<v_rd_off(D0, 0, 0)>(vb), h0 = tr_read<v_rd_off(D0, 0, 1)>(vb), l1 = tr_read<v_rd_off(D0, 1, 0)>(vb), h1 = tr_read<v_rd_off(D0, 1, 1)>(vb);
;   const s16x4 l2 = tr_read<v_rd_off(D0, 2, 0)>(vb), h2 = tr_read<v_rd_off(D0, 2, 1)>(vb), l3 = tr_read<v_rd_off(D0, 3, 0)>(vb), h3 = tr_read<v_rd_off(D0, 3, 1)>(vb);
;   asm volatile("s_waitcnt lgkmcnt(0)" ::: "memory"); SBAR();
;     ...
;   od = __builtin_amdgcn_mfma_f32_32x32x16_bf16(PK(l0, h0), pa0, od, 0, 0, 0);
;   od = __builtin_amdgcn_mfma_f32_32x32x16_bf16(PK(l1, h1), pa1, od, 0, 0, 0);
;   od = __builtin_amdgcn_mfma_f32_32x32x16_bf16(PK(l2, h2), pa2, od, 0, 0, 0);
;   od = __builtin_amdgcn_mfma_f32_32x32x16_bf16(PK(l3, h3), pa3, od, 0, 0, 0);
;     ...
; }
	v_mfma_f32_32x32x16_bf16 v[0:15], v[200:203], v[144:147], v[0:15]
	ds_read_b64_tr_b16 v[200:201], v196 offset:0x200
	ds_read_b64_tr_b16 v[202:203], v196 offset:0xa00
	s_waitcnt lgkmcnt(6)
	v_mfma_f32_32x32x16_bf16 v[0:15], v[204:207], v[148:151], v[0:15]
	ds_read_b64_tr_b16 v[204:205], v196 offset:0x1200
	ds_read_b64_tr_b16 v[206:207], v196 offset:0x1a00
	s_waitcnt lgkmcnt(6)
	v_mfma_f32_32x32x16_bf16 v[0:15], v[208:211], v[152:155], v[0:15]
	ds_read_b64_tr_b16 v[208:209], v196 offset:0x2200
	ds_read_b64_tr_b16 v[210:211], v196 offset:0x2a00
	s_waitcnt lgkmcnt(6)
	v_mfma_f32_32x32x16_bf16 v[0:15], v[212:215], v[170:173], v[0:15]
	ds_read_b64_tr_b16 v[212:213], v196 offset:0x3200
	ds_read_b64_tr_b16 v[214:215], v196 offset:0x3a00
	s_waitcnt lgkmcnt(6)
	v_mfma_f32_32x32x16_bf16 v[48:63], v[200:203], v[144:147], v[48:63]
	ds_read_b64_tr_b16 v[200:201], v196 offset:0x400
	ds_read_b64_tr_b16 v[202:203], v196 offset:0xc00
	s_waitcnt lgkmcnt(6)
	v_mfma_f32_32x32x16_bf16 v[48:63], v[204:207], v[148:151], v[48:63]
	ds_read_b64_tr_b16 v[204:205], v196 offset:0x1400
	ds_read_b64_tr_b16 v[206:207], v196 offset:0x1c00
	s_waitcnt lgkmcnt(6)
	v_mfma_f32_32x32x16_bf16 v[48:63], v[208:211], v[152:155], v[48:63]
	ds_read_b64_tr_b16 v[208:209], v196 offset:0x2400
	ds_read_b64_tr_b16 v[210:211], v196 offset:0x2c00
	s_waitcnt lgkmcnt(6)
	v_mfma_f32_32x32x16_bf16 v[48:63], v[212:215], v[170:173], v[48:63]
	ds_read_b64_tr_b16 v[212:213], v196 offset:0x3400
	ds_read_b64_tr_b16 v[214:215], v196 offset:0x3c00
	s_waitcnt lgkmcnt(6)
	v_mfma_f32_32x32x16_bf16 v[32:47], v[200:203], v[144:147], v[32:47]
	ds_read_b64_tr_b16 v[200:201], v196 offset:0x600
	ds_read_b64_tr_b16 v[202:203], v196 offset:0xe00
	s_waitcnt lgkmcnt(6)
	v_mfma_f32_32x32x16_bf16 v[32:47], v[204:207], v[148:151], v[32:47]
	ds_read_b64_tr_b16 v[204:205], v196 offset:0x1600
	ds_read_b64_tr_b16 v[206:207], v196 offset:0x1e00
	s_waitcnt lgkmcnt(6)
	v_mfma_f32_32x32x16_bf16 v[32:47], v[208:211], v[152:155], v[32:47]
	ds_read_b64_tr_b16 v[208:209], v196 offset:0x2600
	ds_read_b64_tr_b16 v[210:211], v196 offset:0x2e00
	s_waitcnt lgkmcnt(6)
	v_mfma_f32_32x32x16_bf16 v[32:47], v[212:215], v[170:173], v[32:47]
	ds_read_b64_tr_b16 v[212:213], v196 offset:0x3600
	ds_read_b64_tr_b16 v[214:215], v196 offset:0x3e00
	s_waitcnt lgkmcnt(6)
	v_mfma_f32_32x32x16_bf16 v[16:31], v[200:203], v[144:147], v[16:31]
	v_max_f32_e32 v144, v80, v81
	v_max3_f32 v144, v144, v82, v83
	v_max3_f32 v144, v144, v84, v85
	v_max3_f32 v144, v144, v86, v87
	v_max3_f32 v144, v144, v88, v89
	v_max3_f32 v144, v144, v90, v91
	v_max3_f32 v144, v144, v92, v93
	s_waitcnt lgkmcnt(4)
	v_mfma_f32_32x32x16_bf16 v[16:31], v[204:207], v[148:151], v[16:31]
	v_max3_f32 v144, v144, v94, v95
	v_max3_f32 v144, v144, v64, v65
	v_max3_f32 v144, v144, v66, v67
	v_max3_f32 v144, v144, v68, v69
	v_max3_f32 v144, v144, v70, v71
	v_max3_f32 v144, v144, v72, v73
	v_max3_f32 v144, v144, v74, v75
	v_max3_f32 v144, v144, v76, v77
	s_waitcnt lgkmcnt(2)
	v_mfma_f32_32x32x16_bf16 v[16:31], v[208:211], v[152:155], v[16:31]
	v_max3_f32 v144, v144, v78, v79
	v_mov_b32_e32 v145, v144
	s_nop 1
	v_permlane32_swap_b32_e32 v144, v145
	v_max_f32_e32 v144, v144, v145
	v_cmp_ge_f32_e32 vcc, s63, v144
	s_waitcnt lgkmcnt(0)
	v_mfma_f32_32x32x16_bf16 v[16:31], v[212:215], v[170:173], v[16:31]
	s_waitcnt vmcnt(0) lgkmcnt(0)
	s_barrier
	s_cmp_eq_u64 vcc, exec
	s_cbranch_scc1 .Lal_c_m1
	v_max_f32_e32 v242, 0, v144
	v_exp_f32_e64 v152, -v242
	s_nop 0
	v_pk_mul_f32 v[14:15], v[14:15], v[152:153] op_sel_hi:[1,0]
	v_pk_mul_f32 v[12:13], v[12:13], v[152:153] op_sel_hi:[1,0]
	v_pk_mul_f32 v[10:11], v[10:11], v[152:153] op_sel_hi:[1,0]
	v_pk_mul_f32 v[8:9], v[8:9], v[152:153] op_sel_hi:[1,0]
	v_pk_mul_f32 v[6:7], v[6:7], v[152:153] op_sel_hi:[1,0]
	v_pk_mul_f32 v[4:5], v[4:5], v[152:153] op_sel_hi:[1,0]
	v_pk_mul_f32 v[2:3], v[2:3], v[152:153] op_sel_hi:[1,0]
	v_pk_mul_f32 v[0:1], v[0:1], v[152:153] op_sel_hi:[1,0]
	v_pk_mul_f32 v[62:63], v[62:63], v[152:153] op_sel_hi:[1,0]
	v_pk_mul_f32 v[60:61], v[60:61], v[152:153] op_sel_hi:[1,0]
	v_pk_mul_f32 v[58:59], v[58:59], v[152:153] op_sel_hi:[1,0]
	v_pk_mul_f32 v[56:57], v[56:57], v[152:153] op_sel_hi:[1,0]
	v_pk_mul_f32 v[54:55], v[54:55], v[152:153] op_sel_hi:[1,0]
	v_pk_mul_f32 v[52:53], v[52:53], v[152:153] op_sel_hi:[1,0]
	v_pk_mul_f32 v[50:51], v[50:51], v[152:153] op_sel_hi:[1,0]
	v_pk_mul_f32 v[48:49], v[48:49], v[152:153] op_sel_hi:[1,0]
	v_pk_mul_f32 v[46:47], v[46:47], v[152:153] op_sel_hi:[1,0]
	v_pk_mul_f32 v[44:45], v[44:45], v[152:153] op_sel_hi:[1,0]
	v_pk_mul_f32 v[42:43], v[42:43], v[152:153] op_sel_hi:[1,0]
	v_pk_mul_f32 v[40:41], v[40:41], v[152:153] op_sel_hi:[1,0]
	v_pk_mul_f32 v[38:39], v[38:39], v[152:153] op_sel_hi:[1,0]
	v_pk_mul_f32 v[36:37], v[36:37], v[152:153] op_sel_hi:[1,0]
	v_pk_mul_f32 v[34:35], v[34:35], v[152:153] op_sel_hi:[1,0]
	v_pk_mul_f32 v[32:33], v[32:33], v[152:153] op_sel_hi:[1,0]
	v_pk_mul_f32 v[30:31], v[30:31], v[152:153] op_sel_hi:[1,0]
	v_pk_mul_f32 v[28:29], v[28:29], v[152:153] op_sel_hi:[1,0]
	v_pk_mul_f32 v[26:27], v[26:27], v[152:153] op_sel_hi:[1,0]
	v_pk_mul_f32 v[24:25], v[24:25], v[152:153] op_sel_hi:[1,0]
	v_pk_mul_f32 v[22:23], v[22:23], v[152:153] op_sel_hi:[1,0]
	v_pk_mul_f32 v[20:21], v[20:21], v[152:153] op_sel_hi:[1,0]
	v_pk_mul_f32 v[18:19], v[18:19], v[152:153] op_sel_hi:[1,0]
	v_pk_mul_f32 v[16:17], v[16:17], v[152:153] op_sel_hi:[1,0]
	v_sub_f32_e32 v80, v80, v242
	v_sub_f32_e32 v81, v81, v242
	v_sub_f32_e32 v82, v82, v242
	v_sub_f32_e32 v83, v83, v242
	v_sub_f32_e32 v84, v84, v242
	v_sub_f32_e32 v85, v85, v242
	v_sub_f32_e32 v86, v86, v242
	v_sub_f32_e32 v87, v87, v242
	v_sub_f32_e32 v88, v88, v242
	v_sub_f32_e32 v89, v89, v242
	v_sub_f32_e32 v90, v90, v242
	v_sub_f32_e32 v91, v91, v242
	v_sub_f32_e32 v92, v92, v242
	v_sub_f32_e32 v93, v93, v242
	v_sub_f32_e32 v94, v94, v242
	v_sub_f32_e32 v95, v95, v242
	v_sub_f32_e32 v64, v64, v242
	v_sub_f32_e32 v65, v65, v242
	v_sub_f32_e32 v66, v66, v242
	v_sub_f32_e32 v67, v67, v242
	v_sub_f32_e32 v68, v68, v242
	v_sub_f32_e32 v69, v69, v242
	v_sub_f32_e32 v70, v70, v242
	v_sub_f32_e32 v71, v71, v242
	v_sub_f32_e32 v72, v72, v242
	v_sub_f32_e32 v73, v73, v242
	v_sub_f32_e32 v74, v74, v242
	v_sub_f32_e32 v75, v75, v242
	v_sub_f32_e32 v76, v76, v242
	v_sub_f32_e32 v77, v77, v242
	v_sub_f32_e32 v78, v78, v242
	v_sub_f32_e32 v79, v79, v242
	v_sub_f32_e32 v226, v226, v242
	v_sub_f32_e32 v227, v227, v242
	v_sub_f32_e32 v228, v228, v242
	v_sub_f32_e32 v229, v229, v242
	v_sub_f32_e32 v230, v230, v242
	v_sub_f32_e32 v231, v231, v242
	v_sub_f32_e32 v232, v232, v242
	v_sub_f32_e32 v233, v233, v242
	v_sub_f32_e32 v234, v234, v242
	v_sub_f32_e32 v235, v235, v242
	v_sub_f32_e32 v236, v236, v242
	v_sub_f32_e32 v237, v237, v242
	v_sub_f32_e32 v238, v238, v242
	v_sub_f32_e32 v239, v239, v242
	v_sub_f32_e32 v240, v240, v242
	v_sub_f32_e32 v241, v241, v242
	s_branch .LBB0_117

; __device__ __forceinline__ void finishSM(f32x16& p0, f32x16& p1, float alpha, float& l_reg, bf16x8& pa0, bf16x8& pa1, bf16x8& pa2, bf16x8& pa3) {
; #pragma unroll
;   for (int r = 0; r < 16; ++r) p1[r] = __builtin_amdgcn_exp2f(p1[r]);
;   float ps = 0;
; #pragma unroll
;   for (int r = 0; r < 16; ++r) ps += p0[r];
; #pragma unroll
;   for (int r = 0; r < 16; ++r) ps += p1[r];
;   { auto rr = __builtin_amdgcn_permlane32_swap(__float_as_uint(ps), __float_as_uint(ps), false, false);
;     ps = __uint_as_float(rr[0]) + __uint_as_float(rr[1]); }
;   l_reg = l_reg * alpha + ps;
;     ...
;   PK4(p0, 0, pa0); PK4(p0, 8, pa1); PK4(p1, 0, pa2); PK4(p1, 8, pa3);
;     ...
; }
; template <int BUFOFF>
; __device__ __forceinline__ void qkt_mla(f32x16& p0, f32x16& p1, const int* ka, const bf16x8* qr, const char* qlds) {
;   typedef __attribute__((address_space(3))) const bf16x8* lp;
;   p0 = f32x16{}; p1 = f32x16{};
; #pragma unroll
;   for (int d0 = 0; d0 < 12; ++d0) {
;     const int a = ka[d0 & 3] + (d0 >> 2) * 128 + BUFOFF;
;     const bf16x8 b0 = *(lp)(a), b1 = *(lp)(a + 12288);
;     bf16x8 qf;
;     qf = qr[d0];
;     p0 = __builtin_amdgcn_mfma_f32_32x32x16_bf16(b0, qf, p0, 0, 0, 0);
;     p1 = __builtin_amdgcn_mfma_f32_32x32x16_bf16(b1, qf, p1, 0, 0, 0);
;   }
; }
.LBB0_117:
	v_exp_f32_e32 v155, v64
	v_exp_f32_e32 v170, v65
	v_exp_f32_e32 v171, v66
	v_exp_f32_e32 v172, v67
	v_exp_f32_e32 v173, v68
	v_exp_f32_e32 v197, v69
	v_exp_f32_e32 v199, v70
	v_exp_f32_e32 v200, v71
	v_exp_f32_e32 v201, v72
	v_exp_f32_e32 v202, v73
	v_exp_f32_e32 v203, v74
	v_exp_f32_e32 v204, v75
	v_exp_f32_e32 v205, v76
	v_exp_f32_e32 v222, v77
	v_exp_f32_e32 v223, v78
	v_exp_f32_e32 v154, v79
	v_exp_f32_e32 v206, v80
	v_exp_f32_e32 v207, v81
	v_exp_f32_e32 v208, v82
	v_exp_f32_e32 v209, v83
	v_exp_f32_e32 v210, v84
	v_exp_f32_e32 v211, v85
	v_exp_f32_e32 v212, v86
	v_exp_f32_e32 v213, v87
	v_exp_f32_e32 v214, v88
	v_exp_f32_e32 v215, v89
	v_exp_f32_e32 v216, v90
	v_exp_f32_e32 v217, v91
	v_exp_f32_e32 v218, v92
	v_exp_f32_e32 v219, v93
	v_exp_f32_e32 v220, v94
	v_exp_f32_e32 v221, v95
	ds_read_b128 v[64:67], v169
	ds_read_b128 v[68:71], v169 offset:12288
	ds_read_b128 v[144:147], v190
	ds_read_b128 v[148:151], v190 offset:12288
	v_mov_b32_e32 v224, v155
	s_waitcnt lgkmcnt(0)
	v_mfma_f32_32x32x16_bf16 v[80:95], v[64:67], v[140:143], v[226:241]
	v_mfma_f32_32x32x16_bf16 v[64:79], v[68:71], v[140:143], v[226:241]
	v_mov_b32_e32 v225, v154
	v_mfma_f32_32x32x16_bf16 v[80:95], v[144:147], v[136:139], v[80:95]
	v_mfma_f32_32x32x16_bf16 v[64:79], v[148:151], v[136:139], v[64:79]
	ds_read_b128 v[144:147], v193
	ds_read_b128 v[148:151], v193 offset:12288
	s_waitcnt lgkmcnt(0)
	v_mfma_f32_32x32x16_bf16 v[80:95], v[144:147], v[132:135], v[80:95]
	v_mfma_f32_32x32x16_bf16 v[64:79], v[148:151], v[132:135], v[64:79]
	ds_read_b128 v[144:147], v192
	ds_read_b128 v[148:151], v192 offset:12288
	s_waitcnt lgkmcnt(0)
	v_mfma_f32_32x32x16_bf16 v[80:95], v[144:147], v[128:131], v[80:95]
	v_mfma_f32_32x32x16_bf16 v[64:79], v[148:151], v[128:131], v[64:79]
	ds_read_b128 v[144:147], v169 offset:128
	ds_read_b128 v[148:151], v169 offset:12416
	s_waitcnt lgkmcnt(0)
	v_mfma_f32_32x32x16_bf16 v[80:95], v[144:147], v[124:127], v[80:95]
	v_mfma_f32_32x32x16_bf16 v[64:79], v[148:151], v[124:127], v[64:79]
	ds_read_b128 v[144:147], v190 offset:128
	ds_read_b128 v[148:151], v190 offset:12416
	s_waitcnt lgkmcnt(0)
	v_mfma_f32_32x32x16_bf16 v[80:95], v[144:147], v[120:123], v[80:95]
	v_mfma_f32_32x32x16_bf16 v[64:79], v[148:151], v[120:123], v[64:79]
	ds_read_b128 v[144:147], v193 offset:128
	ds_read_b128 v[148:151], v193 offset:12416
	s_waitcnt lgkmcnt(0)
	v_mfma_f32_32x32x16_bf16 v[80:95], v[144:147], v[116:119], v[80:95]
	v_mfma_f32_32x32x16_bf16 v[64:79], v[148:151], v[116:119], v[64:79]
	ds_read_b128 v[144:147], v192 offset:128
	ds_read_b128 v[148:151], v192 offset:12416
	s_waitcnt lgkmcnt(0)
	v_mfma_f32_32x32x16_bf16 v[80:95], v[144:147], v[112:115], v[80:95]
	v_mfma_f32_32x32x16_bf16 v[64:79], v[148:151], v[112:115], v[64:79]
	ds_read_b128 v[144:147], v169 offset:256
	ds_read_b128 v[148:151], v169 offset:12544
	s_waitcnt lgkmcnt(0)
	v_mfma_f32_32x32x16_bf16 v[80:95], v[144:147], v[108:111], v[80:95]
	v_mfma_f32_32x32x16_bf16 v[64:79], v[148:151], v[108:111], v[64:79]
	ds_read_b128 v[144:147], v190 offset:256
	ds_read_b128 v[148:151], v190 offset:12544
	s_waitcnt lgkmcnt(0)
	v_mfma_f32_32x32x16_bf16 v[80:95], v[144:147], v[104:107], v[80:95]
	v_mfma_f32_32x32x16_bf16 v[64:79], v[148:151], v[104:107], v[64:79]
	ds_read_b128 v[144:147], v193 offset:256
	ds_read_b128 v[148:151], v193 offset:12544
	s_waitcnt lgkmcnt(0)
	v_mfma_f32_32x32x16_bf16 v[80:95], v[144:147], v[100:103], v[80:95]
	v_mfma_f32_32x32x16_bf16 v[64:79], v[148:151], v[100:103], v[64:79]
	ds_read_b128 v[144:147], v192 offset:256
	ds_read_b128 v[148:151], v192 offset:12544
	s_waitcnt lgkmcnt(0)
	v_mfma_f32_32x32x16_bf16 v[80:95], v[144:147], v[96:99], v[80:95]
	v_add_f32_e32 v144, v214, v206
	v_add_f32_e32 v243, v215, v207
	v_add_f32_e32 v244, v216, v208
	v_add_f32_e32 v245, v217, v209
	v_add_f32_e32 v246, v218, v210
	v_add_f32_e32 v247, v219, v211
	v_add_f32_e32 v251, v220, v212
	v_add_f32_e32 v252, v221, v213
	v_add_f32_e32 v144, v224, v144
	v_add_f32_e32 v243, v170, v243
	v_add_f32_e32 v244, v171, v244
	v_add_f32_e32 v245, v172, v245
	v_add_f32_e32 v246, v173, v246
	v_add_f32_e32 v247, v197, v247
	v_add_f32_e32 v251, v199, v251
	v_add_f32_e32 v252, v200, v252
	v_add_f32_e32 v144, v201, v144
	v_add_f32_e32 v243, v202, v243
	v_mfma_f32_32x32x16_bf16 v[64:79], v[148:151], v[96:99], v[64:79]
	v_add_f32_e32 v244, v203, v244
	v_add_f32_e32 v245, v204, v245
	v_add_f32_e32 v246, v205, v246
	v_add_f32_e32 v247, v222, v247
	v_add_f32_e32 v251, v223, v251
	v_add_f32_e32 v252, v225, v252
	v_add_f32_e32 v144, v144, v243
	v_add_f32_e32 v244, v244, v245
	v_add_f32_e32 v246, v246, v247
	v_add_f32_e32 v251, v251, v252
	v_add_f32_e32 v144, v144, v244
	v_add_f32_e32 v246, v246, v251
	v_add_f32_e32 v154, v144, v246
	v_mov_b32_e32 v155, v154
	v_cvt_pk_bf16_f32 v144, v206, v207
	v_cvt_pk_bf16_f32 v145, v208, v209
	v_cvt_pk_bf16_f32 v146, v210, v211
	v_cvt_pk_bf16_f32 v147, v212, v213
	s_nop 1
	v_permlane32_swap_b32_e32 v154, v155
	v_cvt_pk_bf16_f32 v148, v214, v215
	v_cvt_pk_bf16_f32 v149, v216, v217
	v_cvt_pk_bf16_f32 v150, v218, v219
	v_cvt_pk_bf16_f32 v151, v220, v221
	v_cvt_pk_bf16_f32 v170, v224, v170
	v_cvt_pk_bf16_f32 v171, v171, v172
	v_cvt_pk_bf16_f32 v172, v173, v197
	v_cvt_pk_bf16_f32 v173, v199, v200
	v_cvt_pk_bf16_f32 v200, v201, v202
	v_cvt_pk_bf16_f32 v201, v203, v204
	v_cvt_pk_bf16_f32 v202, v205, v222
	v_cvt_pk_bf16_f32 v203, v223, v225
	s_nop 0
	s_add_u32 s4, s56, 0x17090000
	s_addc_u32 s5, s57, 0
	s_add_u32 s56, s58, 0x1a060000
	s_mov_b32 m0, s16
	s_addc_u32 s57, s59, 0
	s_add_i32 s58, s40, s60
	global_load_lds_dwordx4 v188, s[4:5]
	s_mov_b32 m0, s17
	s_nop 0
	global_load_lds_dwordx4 v189, s[4:5]
	s_mov_b32 m0, s44
	s_nop 0
	global_load_lds_dwordx4 v191, s[4:5]
	s_mov_b32 m0, s58
	s_nop 0
	global_load_lds_dwordx4 v194, s[56:57]
	s_add_i32 m0, s58, 0x2000
	s_nop 0
	global_load_lds_dwordx4 v195, s[56:57]
	v_lshl_add_u32 v197, s55, 14, v167
	ds_read_b64_tr_b16 v[204:205], v197 offset:0
	ds_read_b64_tr_b16 v[206:207], v197 offset:0x800
	ds_read_b64_tr_b16 v[208:209], v197 offset:0x1000
	ds_read_b64_tr_b16 v[210:211], v197 offset:0x1800
	ds_read_b64_tr_b16 v[212:213], v197 offset:0x2000
	ds_read_b64_tr_b16 v[214:215], v197 offset:0x2800
	ds_read_b64_tr_b16 v[216:217], v197 offset:0x3000
	ds_read_b64_tr_b16 v[218:219], v197 offset:0x3800
	s_nop 0
	s_waitcnt lgkmcnt(6)
; #define SBAR() __builtin_amdgcn_sched_barrier(0)
; template <int MLA>
; __device__ __forceinline__ void partialSM(f32x16& p0, f32x16& p1, float& m_reg, float& mn, float& alpha) {
;     ...
;   float pmax = p0[0];
; #pragma unroll
;   for (int r = 1; r < 16; ++r) pmax = fmaxf(pmax, p0[r]);
; #pragma unroll
;   for (int r = 0; r < 16; ++r) pmax = fmaxf(pmax, p1[r]);
;   { auto rr = __builtin_amdgcn_permlane32_swap(__float_as_uint(pmax), __float_as_uint(pmax), false, false);
;     pmax = fmaxf(__uint_as_float(rr[0]), __uint_as_float(rr[1])); }
;   if (__builtin_expect(__all(pmax - m_reg <= THR / SCALE), 1)) { mn = m_reg; alpha = 1.f; }
;   else { mn = fmaxf(m_reg, pmax); alpha = __builtin_amdgcn_exp2f((m_reg - mn) * C); m_reg = mn; }
;   float mnC = -mn * C;
; #pragma unroll
;   for (int r = 0; r < 16; ++r) p0[r] = fmaf(p0[r], C, mnC);
; #pragma unroll
;   for (int r = 0; r < 16; ++r) p1[r] = fmaf(p1[r], C, mnC);
; #pragma unroll
;   for (int r = 0; r < 16; ++r) p0[r] = __builtin_amdgcn_exp2f(p0[r]);
; }
; template <int D0> __device__ __forceinline__ void pv_one_t(f32x16& od, int vb, bf16x8 pa0, bf16x8 pa1, bf16x8 pa2, bf16x8 pa3) {
;   const s16x4 l0 = tr_read<v_rd_off(D0, 0, 0)>(vb), h0 = tr_read<v_rd_off(D0, 0, 1)>(vb), l1 = tr_read<v_rd_off(D0, 1, 0)>(vb), h1 = tr_read<v_rd_off(D0, 1, 1)>(vb);
;   const s16x4 l2 = tr_read<v_rd_off(D0, 2, 0)>(vb), h2 = tr_read<v_rd_off(D0, 2, 1)>(vb), l3 = tr_read<v_rd_off(D0, 3, 0)>(vb), h3 = tr_read<v_rd_off(D0, 3, 1)>(vb);
;   asm volatile("s_waitcnt lgkmcnt(0)" ::: "memory"); SBAR();
;     ...
;   od = __builtin_amdgcn_mfma_f32_32x32x16_bf16(PK(l0, h0), pa0, od, 0, 0, 0);
;   od = __builtin_amdgcn_mfma_f32_32x32x16_bf16(PK(l1, h1), pa1, od, 0, 0, 0);
;   od = __builtin_amdgcn_mfma_f32_32x32x16_bf16(PK(l2, h2), pa2, od, 0, 0, 0);
;   od = __builtin_amdgcn_mfma_f32_32x32x16_bf16(PK(l3, h3), pa3, od, 0, 0, 0);
;     ...
; }
	v_mfma_f32_32x32x16_bf16 v[0:15], v[204:207], v[144:147], v[0:15]
	ds_read_b64_tr_b16 v[204:205], v197 offset:0x200
	ds_read_b64_tr_b16 v[206:207], v197 offset:0xa00
	s_waitcnt lgkmcnt(6)
	v_mfma_f32_32x32x16_bf16 v[0:15], v[208:211], v[148:151], v[0:15]
	ds_read_b64_tr_b16 v[208:209], v197 offset:0x1200
	ds_read_b64_tr_b16 v[210:211], v197 offset:0x1a00
	s_waitcnt lgkmcnt(6)
	v_mfma_f32_32x32x16_bf16 v[0:15], v[212:215], v[170:173], v[0:15]
	ds_read_b64_tr_b16 v[212:213], v197 offset:0x2200
	ds_read_b64_tr_b16 v[214:215], v197 offset:0x2a00
	s_waitcnt lgkmcnt(6)
	v_mfma_f32_32x32x16_bf16 v[0:15], v[216:219], v[200:203], v[0:15]
	ds_read_b64_tr_b16 v[216:217], v197 offset:0x3200
	ds_read_b64_tr_b16 v[218:219], v197 offset:0x3a00
	s_waitcnt lgkmcnt(6)
	v_mfma_f32_32x32x16_bf16 v[48:63], v[204:207], v[144:147], v[48:63]
	ds_read_b64_tr_b16 v[204:205], v197 offset:0x400
	ds_read_b64_tr_b16 v[206:207], v197 offset:0xc00
	s_waitcnt lgkmcnt(6)
	v_mfma_f32_32x32x16_bf16 v[48:63], v[208:211], v[148:151], v[48:63]
	ds_read_b64_tr_b16 v[208:209], v197 offset:0x1400
	ds_read_b64_tr_b16 v[210:211], v197 offset:0x1c00
	s_waitcnt lgkmcnt(6)
	v_mfma_f32_32x32x16_bf16 v[48:63], v[212:215], v[170:173], v[48:63]
	ds_read_b64_tr_b16 v[212:213], v197 offset:0x2400
	ds_read_b64_tr_b16 v[214:215], v197 offset:0x2c00
	s_waitcnt lgkmcnt(6)
	v_mfma_f32_32x32x16_bf16 v[48:63], v[216:219], v[200:203], v[48:63]
	ds_read_b64_tr_b16 v[216:217], v197 offset:0x3400
	ds_read_b64_tr_b16 v[218:219], v197 offset:0x3c00
	s_waitcnt lgkmcnt(6)
	v_mfma_f32_32x32x16_bf16 v[32:47], v[204:207], v[144:147], v[32:47]
	ds_read_b64_tr_b16 v[204:205], v197 offset:0x600
	ds_read_b64_tr_b16 v[206:207], v197 offset:0xe00
	s_waitcnt lgkmcnt(6)
	v_mfma_f32_32x32x16_bf16 v[32:47], v[208:211], v[148:151], v[32:47]
	ds_read_b64_tr_b16 v[208:209], v197 offset:0x1600
	ds_read_b64_tr_b16 v[210:211], v197 offset:0x1e00
	s_waitcnt lgkmcnt(6)
	v_mfma_f32_32x32x16_bf16 v[32:47], v[212:215], v[170:173], v[32:47]
	ds_read_b64_tr_b16 v[212:213], v197 offset:0x2600
	ds_read_b64_tr_b16 v[214:215], v197 offset:0x2e00
	s_waitcnt lgkmcnt(6)
	v_mfma_f32_32x32x16_bf16 v[32:47], v[216:219], v[200:203], v[32:47]
	ds_read_b64_tr_b16 v[216:217], v197 offset:0x3600
	ds_read_b64_tr_b16 v[218:219], v197 offset:0x3e00
	s_waitcnt lgkmcnt(6)
	v_mfma_f32_32x32x16_bf16 v[16:31], v[204:207], v[144:147], v[16:31]
	v_max_f32_e32 v144, v80, v81
	v_max3_f32 v144, v144, v82, v83
	v_max3_f32 v144, v144, v84, v85
	v_max3_f32 v144, v144, v86, v87
	v_max3_f32 v144, v144, v88, v89
	v_max3_f32 v144, v144, v90, v91
	v_max3_f32 v144, v144, v92, v93
	s_waitcnt lgkmcnt(4)
	v_mfma_f32_32x32x16_bf16 v[16:31], v[208:211], v[148:151], v[16:31]
	v_max3_f32 v144, v144, v94, v95
	v_max3_f32 v144, v144, v64, v65
	v_max3_f32 v144, v144, v66, v67
	v_max3_f32 v144, v144, v68, v69
	v_max3_f32 v144, v144, v70, v71
	v_max3_f32 v144, v144, v72, v73
	v_max3_f32 v144, v144, v74, v75
	v_max3_f32 v144, v144, v76, v77
	s_waitcnt lgkmcnt(2)
	v_mfma_f32_32x32x16_bf16 v[16:31], v[212:215], v[170:173], v[16:31]
	v_max3_f32 v144, v144, v78, v79
	v_mov_b32_e32 v145, v144
	s_nop 1
	v_permlane32_swap_b32_e32 v144, v145
	v_max_f32_e32 v144, v144, v145
	v_cmp_ge_f32_e32 vcc, s63, v144
	s_waitcnt lgkmcnt(0)
	v_mfma_f32_32x32x16_bf16 v[16:31], v[216:219], v[200:203], v[16:31]
	s_waitcnt vmcnt(0) lgkmcnt(0)
	s_barrier
	s_cmp_eq_u64 vcc, exec
	s_cbranch_scc1 .Lal_c_m2
	v_max_f32_e32 v242, 0, v144
	v_exp_f32_e64 v144, -v242
	s_nop 0
	v_pk_mul_f32 v[14:15], v[14:15], v[144:145] op_sel_hi:[1,0]
	v_pk_mul_f32 v[12:13], v[12:13], v[144:145] op_sel_hi:[1,0]
	v_pk_mul_f32 v[10:11], v[10:11], v[144:145] op_sel_hi:[1,0]
	v_pk_mul_f32 v[8:9], v[8:9], v[144:145] op_sel_hi:[1,0]
	v_pk_mul_f32 v[6:7], v[6:7], v[144:145] op_sel_hi:[1,0]
	v_pk_mul_f32 v[4:5], v[4:5], v[144:145] op_sel_hi:[1,0]
	v_pk_mul_f32 v[2:3], v[2:3], v[144:145] op_sel_hi:[1,0]
	v_pk_mul_f32 v[0:1], v[0:1], v[144:145] op_sel_hi:[1,0]
	v_pk_mul_f32 v[62:63], v[62:63], v[144:145] op_sel_hi:[1,0]
	v_pk_mul_f32 v[60:61], v[60:61], v[144:145] op_sel_hi:[1,0]
	v_pk_mul_f32 v[58:59], v[58:59], v[144:145] op_sel_hi:[1,0]
	v_pk_mul_f32 v[56:57], v[56:57], v[144:145] op_sel_hi:[1,0]
	v_pk_mul_f32 v[54:55], v[54:55], v[144:145] op_sel_hi:[1,0]
	v_pk_mul_f32 v[52:53], v[52:53], v[144:145] op_sel_hi:[1,0]
	v_pk_mul_f32 v[50:51], v[50:51], v[144:145] op_sel_hi:[1,0]
	v_pk_mul_f32 v[48:49], v[48:49], v[144:145] op_sel_hi:[1,0]
	v_pk_mul_f32 v[46:47], v[46:47], v[144:145] op_sel_hi:[1,0]
	v_pk_mul_f32 v[44:45], v[44:45], v[144:145] op_sel_hi:[1,0]
	v_pk_mul_f32 v[42:43], v[42:43], v[144:145] op_sel_hi:[1,0]
	v_pk_mul_f32 v[40:41], v[40:41], v[144:145] op_sel_hi:[1,0]
	v_pk_mul_f32 v[38:39], v[38:39], v[144:145] op_sel_hi:[1,0]
	v_pk_mul_f32 v[36:37], v[36:37], v[144:145] op_sel_hi:[1,0]
	v_pk_mul_f32 v[34:35], v[34:35], v[144:145] op_sel_hi:[1,0]
	v_pk_mul_f32 v[32:33], v[32:33], v[144:145] op_sel_hi:[1,0]
	v_pk_mul_f32 v[30:31], v[30:31], v[144:145] op_sel_hi:[1,0]
	v_pk_mul_f32 v[28:29], v[28:29], v[144:145] op_sel_hi:[1,0]
	v_pk_mul_f32 v[26:27], v[26:27], v[144:145] op_sel_hi:[1,0]
	v_pk_mul_f32 v[24:25], v[24:25], v[144:145] op_sel_hi:[1,0]
	v_pk_mul_f32 v[22:23], v[22:23], v[144:145] op_sel_hi:[1,0]
	v_pk_mul_f32 v[20:21], v[20:21], v[144:145] op_sel_hi:[1,0]
	v_pk_mul_f32 v[18:19], v[18:19], v[144:145] op_sel_hi:[1,0]
	v_pk_mul_f32 v[16:17], v[16:17], v[144:145] op_sel_hi:[1,0]
	v_sub_f32_e32 v80, v80, v242
	v_sub_f32_e32 v81, v81, v242
	v_sub_f32_e32 v82, v82, v242
	v_sub_f32_e32 v83, v83, v242
	v_sub_f32_e32 v84, v84, v242
	v_sub_f32_e32 v85, v85, v242
	v_sub_f32_e32 v86, v86, v242
	v_sub_f32_e32 v87, v87, v242
	v_sub_f32_e32 v88, v88, v242
	v_sub_f32_e32 v89, v89, v242
	v_sub_f32_e32 v90, v90, v242
	v_sub_f32_e32 v91, v91, v242
	v_sub_f32_e32 v92, v92, v242
	v_sub_f32_e32 v93, v93, v242
	v_sub_f32_e32 v94, v94, v242
	v_sub_f32_e32 v95, v95, v242
	v_sub_f32_e32 v64, v64, v242
	v_sub_f32_e32 v65, v65, v242
	v_sub_f32_e32 v66, v66, v242
	v_sub_f32_e32 v67, v67, v242
	v_sub_f32_e32 v68, v68, v242
	v_sub_f32_e32 v69, v69, v242
	v_sub_f32_e32 v70, v70, v242
	v_sub_f32_e32 v71, v71, v242
	v_sub_f32_e32 v72, v72, v242
	v_sub_f32_e32 v73, v73, v242
	v_sub_f32_e32 v74, v74, v242
	v_sub_f32_e32 v75, v75, v242
	v_sub_f32_e32 v76, v76, v242
	v_sub_f32_e32 v77, v77, v242
	v_sub_f32_e32 v78, v78, v242
	v_sub_f32_e32 v79, v79, v242
	v_sub_f32_e32 v226, v226, v242
	v_sub_f32_e32 v227, v227, v242
	v_sub_f32_e32 v228, v228, v242
	v_sub_f32_e32 v229, v229, v242
	v_sub_f32_e32 v230, v230, v242
	v_sub_f32_e32 v231, v231, v242
	v_sub_f32_e32 v232, v232, v242
	v_sub_f32_e32 v233, v233, v242
	v_sub_f32_e32 v234, v234, v242
	v_sub_f32_e32 v235, v235, v242
	v_sub_f32_e32 v236, v236, v242
	v_sub_f32_e32 v237, v237, v242
	v_sub_f32_e32 v238, v238, v242
	v_sub_f32_e32 v239, v239, v242
	v_sub_f32_e32 v240, v240, v242
	v_sub_f32_e32 v241, v241, v242
	s_branch .LBB0_119

; __device__ __forceinline__ void finishSM(f32x16& p0, f32x16& p1, float alpha, float& l_reg, bf16x8& pa0, bf16x8& pa1, bf16x8& pa2, bf16x8& pa3) {
; #pragma unroll
;   for (int r = 0; r < 16; ++r) p1[r] = __builtin_amdgcn_exp2f(p1[r]);
;   float ps = 0;
; #pragma unroll
;   for (int r = 0; r < 16; ++r) ps += p0[r];
; #pragma unroll
;   for (int r = 0; r < 16; ++r) ps += p1[r];
;   { auto rr = __builtin_amdgcn_permlane32_swap(__float_as_uint(ps), __float_as_uint(ps), false, false);
;     ps = __uint_as_float(rr[0]) + __uint_as_float(rr[1]); }
;   l_reg = l_reg * alpha + ps;
;     ...
;   PK4(p0, 0, pa0); PK4(p0, 8, pa1); PK4(p1, 0, pa2); PK4(p1, 8, pa3);
;     ...
; }
; template <int BUFOFF>
; __device__ __forceinline__ void qkt_diff(f32x16& p0, f32x16& p1, const int* ka, const bf16x8* qr) {
;   typedef __attribute__((address_space(3))) const bf16x8* lp;
;   p0 = f32x16{}; p1 = f32x16{};
; #pragma unroll
;   for (int d0 = 0; d0 < 4; ++d0) {
;     const int a = ka[d0] + BUFOFF;
;     const bf16x8 b0 = *(lp)(a), b1 = *(lp)(a + 8192);
;     p0 = __builtin_amdgcn_mfma_f32_32x32x16_bf16(b0, qr[d0], p0, 0, 0, 0);
;     p1 = __builtin_amdgcn_mfma_f32_32x32x16_bf16(b1, qr[d0], p1, 0, 0, 0);
;   }
; }
.LBB0_129:
	s_mov_b32 s54, s47
	s_mov_b32 s47, s52
	ds_read_b128 v[64:67], v138 offset:16384
	ds_read_b128 v[68:71], v138 offset:24576
	ds_read_b128 v[170:173], v141 offset:16384
	ds_read_b128 v[188:191], v141 offset:24576
	s_waitcnt lgkmcnt(0)
	v_mfma_f32_32x32x16_bf16 v[80:95], v[64:67], v[108:111], v[226:241]
	v_add_f32_e32 v112, v144, v113
	v_mfma_f32_32x32x16_bf16 v[64:79], v[68:71], v[108:111], v[226:241]
	v_add_f32_e32 v243, v148, v155
	v_add_f32_e32 v244, v145, v152
	v_add_f32_e32 v245, v149, v156
	v_add_f32_e32 v246, v146, v153
	v_add_f32_e32 v247, v150, v158
	v_mfma_f32_32x32x16_bf16 v[80:95], v[170:173], v[104:107], v[80:95]
	v_add_f32_e32 v251, v147, v154
	v_add_f32_e32 v252, v151, v159
	v_mov_b32_e32 v132, v124
	v_add_f32_e32 v112, v128, v112
	v_mov_b32_e32 v162, v125
	v_mfma_f32_32x32x16_bf16 v[64:79], v[188:191], v[104:107], v[64:79]
	ds_read_b128 v[170:173], v140 offset:16384
	ds_read_b128 v[188:191], v140 offset:24576
	v_add_f32_e32 v243, v129, v243
	v_mov_b32_e32 v167, v120
	v_add_f32_e32 v244, v126, v244
	v_mov_b32_e32 v169, v121
	v_add_f32_e32 v245, v127, v245
	v_add_f32_e32 v246, v132, v246
	s_waitcnt lgkmcnt(0)
	v_mfma_f32_32x32x16_bf16 v[80:95], v[170:173], v[100:103], v[80:95]
	v_add_f32_e32 v247, v162, v247
	v_add_f32_e32 v251, v167, v251
	v_add_f32_e32 v252, v169, v252
	v_mfma_f32_32x32x16_bf16 v[64:79], v[188:191], v[100:103], v[64:79]
	ds_read_b128 v[170:173], v139 offset:16384
	ds_read_b128 v[188:191], v139 offset:24576
	s_waitcnt lgkmcnt(0)
	v_mfma_f32_32x32x16_bf16 v[80:95], v[170:173], v[96:99], v[80:95]
	v_mov_b32_e32 v170, v118
	v_mov_b32_e32 v171, v117
	v_mov_b32_e32 v172, v114
	v_mov_b32_e32 v173, v115
	v_add_f32_e32 v112, v170, v112
	v_add_f32_e32 v243, v119, v243
	v_add_f32_e32 v244, v116, v244
	v_mfma_f32_32x32x16_bf16 v[64:79], v[188:191], v[96:99], v[64:79]
	v_mov_b32_e32 v188, v122
	v_mov_b32_e32 v189, v123
	v_add_f32_e32 v245, v171, v245
	v_add_f32_e32 v246, v172, v246
	v_add_f32_e32 v247, v173, v247
	v_add_f32_e32 v251, v188, v251
	v_add_f32_e32 v252, v189, v252
	v_add_f32_e32 v112, v112, v243
	v_add_f32_e32 v244, v244, v245
	v_add_f32_e32 v246, v246, v247
	v_add_f32_e32 v251, v251, v252
	v_add_f32_e32 v112, v112, v244
	v_add_f32_e32 v246, v246, v251
	v_add_f32_e32 v117, v112, v246
	v_mov_b32_e32 v118, v117
	v_cvt_pk_bf16_f32 v112, v113, v155
	v_cvt_pk_bf16_f32 v113, v152, v156
	v_cvt_pk_bf16_f32 v114, v153, v158
	s_nop 1
	v_permlane32_swap_b32_e32 v117, v118
	v_cvt_pk_bf16_f32 v115, v154, v159
	v_cvt_pk_bf16_f32 v120, v144, v148
	v_cvt_pk_bf16_f32 v121, v145, v149
	v_cvt_pk_bf16_f32 v122, v146, v150
	v_cvt_pk_bf16_f32 v123, v147, v151
	v_cvt_pk_bf16_f32 v124, v128, v129
	v_cvt_pk_bf16_f32 v125, v126, v127
	v_cvt_pk_bf16_f32 v126, v132, v162
	v_cvt_pk_bf16_f32 v127, v167, v169
	v_cvt_pk_bf16_f32 v144, v170, v119
	v_cvt_pk_bf16_f32 v145, v116, v171
	v_cvt_pk_bf16_f32 v146, v172, v173
	v_cvt_pk_bf16_f32 v147, v188, v189
	s_add_u32 s4, s14, 0x2000000
	s_mov_b32 m0, s43
	s_addc_u32 s5, s15, 0
	s_mov_b64 s[56:57], s[14:15]
	s_lshl_b32 s52, s53, 14
	s_add_i32 s55, s42, s52
	s_nop 0
	global_load_lds_dwordx4 v134, s[56:57]
	s_mov_b32 m0, s44
	s_nop 0
	global_load_lds_dwordx4 v135, s[56:57]
	s_mov_b32 m0, s55
	s_nop 0
	global_load_lds_dwordx4 v136, s[4:5]
	s_add_i32 m0, s55, 0x2000
	s_nop 0
	global_load_lds_dwordx4 v137, s[4:5]
	s_lshl_b32 s55, s47, 14
	v_add_u32_e32 v132, s55, v133
	ds_read_b64_tr_b16 v[148:149], v132 offset:0
	ds_read_b64_tr_b16 v[150:151], v132 offset:0x800
	ds_read_b64_tr_b16 v[152:153], v132 offset:0x1000
	ds_read_b64_tr_b16 v[154:155], v132 offset:0x1800
	ds_read_b64_tr_b16 v[170:171], v132 offset:0x2000
	ds_read_b64_tr_b16 v[172:173], v132 offset:0x2800
	ds_read_b64_tr_b16 v[188:189], v132 offset:0x3000
	ds_read_b64_tr_b16 v[190:191], v132 offset:0x3800
	s_nop 0
	s_waitcnt lgkmcnt(6)
	v_mfma_f32_32x32x16_bf16 v[32:47], v[148:151], v[112:115], v[32:47]
	ds_read_b64_tr_b16 v[148:149], v132 offset:0x200
	ds_read_b64_tr_b16 v[150:151], v132 offset:0xa00
	s_waitcnt lgkmcnt(6)
	v_mfma_f32_32x32x16_bf16 v[32:47], v[152:155], v[120:123], v[32:47]
	ds_read_b64_tr_b16 v[152:153], v132 offset:0x1200
	ds_read_b64_tr_b16 v[154:155], v132 offset:0x1a00
	s_waitcnt lgkmcnt(6)
	v_mfma_f32_32x32x16_bf16 v[32:47], v[170:173], v[124:127], v[32:47]
	ds_read_b64_tr_b16 v[170:171], v132 offset:0x2200
	ds_read_b64_tr_b16 v[172:173], v132 offset:0x2a00
	s_waitcnt lgkmcnt(6)
	v_mfma_f32_32x32x16_bf16 v[32:47], v[188:191], v[144:147], v[32:47]
	ds_read_b64_tr_b16 v[188:189], v132 offset:0x3200
	ds_read_b64_tr_b16 v[190:191], v132 offset:0x3a00
	s_waitcnt lgkmcnt(6)
	v_mfma_f32_32x32x16_bf16 v[48:63], v[148:151], v[112:115], v[48:63]
	ds_read_b64_tr_b16 v[148:149], v132 offset:0x400
	ds_read_b64_tr_b16 v[150:151], v132 offset:0xc00
	s_waitcnt lgkmcnt(6)
	v_mfma_f32_32x32x16_bf16 v[48:63], v[152:155], v[120:123], v[48:63]
	ds_read_b64_tr_b16 v[152:153], v132 offset:0x1400
	ds_read_b64_tr_b16 v[154:155], v132 offset:0x1c00
	s_waitcnt lgkmcnt(6)
	v_mfma_f32_32x32x16_bf16 v[48:63], v[170:173], v[124:127], v[48:63]
	ds_read_b64_tr_b16 v[170:171], v132 offset:0x2400
	ds_read_b64_tr_b16 v[172:173], v132 offset:0x2c00
	s_waitcnt lgkmcnt(6)
	v_mfma_f32_32x32x16_bf16 v[48:63], v[188:191], v[144:147], v[48:63]
	ds_read_b64_tr_b16 v[188:189], v132 offset:0x3400
	ds_read_b64_tr_b16 v[190:191], v132 offset:0x3c00
	s_waitcnt lgkmcnt(6)
; #define SBAR() __builtin_amdgcn_sched_barrier(0)
; template <int MLA>
; __device__ __forceinline__ void partialSM(f32x16& p0, f32x16& p1, float& m_reg, float& mn, float& alpha) {
;     ...
;   float pmax = p0[0];
; #pragma unroll
;   for (int r = 1; r < 16; ++r) pmax = fmaxf(pmax, p0[r]);
; #pragma unroll
;   for (int r = 0; r < 16; ++r) pmax = fmaxf(pmax, p1[r]);
;   { auto rr = __builtin_amdgcn_permlane32_swap(__float_as_uint(pmax), __float_as_uint(pmax), false, false);
;     pmax = fmaxf(__uint_as_float(rr[0]), __uint_as_float(rr[1])); }
;   if (__builtin_expect(__all(pmax - m_reg <= THR / SCALE), 1)) { mn = m_reg; alpha = 1.f; }
;   else { mn = fmaxf(m_reg, pmax); alpha = __builtin_amdgcn_exp2f((m_reg - mn) * C); m_reg = mn; }
;   float mnC = -mn * C;
; #pragma unroll
;   for (int r = 0; r < 16; ++r) p0[r] = fmaf(p0[r], C, mnC);
; #pragma unroll
;   for (int r = 0; r < 16; ++r) p1[r] = fmaf(p1[r], C, mnC);
; #pragma unroll
;   for (int r = 0; r < 16; ++r) p0[r] = __builtin_amdgcn_exp2f(p0[r]);
; }
; template <int D0> __device__ __forceinline__ void pv_one_t(f32x16& od, int vb, bf16x8 pa0, bf16x8 pa1, bf16x8 pa2, bf16x8 pa3) {
;   const s16x4 l0 = tr_read<v_rd_off(D0, 0, 0)>(vb), h0 = tr_read<v_rd_off(D0, 0, 1)>(vb), l1 = tr_read<v_rd_off(D0, 1, 0)>(vb), h1 = tr_read<v_rd_off(D0, 1, 1)>(vb);
;   const s16x4 l2 = tr_read<v_rd_off(D0, 2, 0)>(vb), h2 = tr_read<v_rd_off(D0, 2, 1)>(vb), l3 = tr_read<v_rd_off(D0, 3, 0)>(vb), h3 = tr_read<v_rd_off(D0, 3, 1)>(vb);
;   asm volatile("s_waitcnt lgkmcnt(0)" ::: "memory"); SBAR();
;     ...
;   od = __builtin_amdgcn_mfma_f32_32x32x16_bf16(PK(l0, h0), pa0, od, 0, 0, 0);
;   od = __builtin_amdgcn_mfma_f32_32x32x16_bf16(PK(l1, h1), pa1, od, 0, 0, 0);
;   od = __builtin_amdgcn_mfma_f32_32x32x16_bf16(PK(l2, h2), pa2, od, 0, 0, 0);
;   od = __builtin_amdgcn_mfma_f32_32x32x16_bf16(PK(l3, h3), pa3, od, 0, 0, 0);
;     ...
; }
	v_mfma_f32_32x32x16_bf16 v[16:31], v[148:151], v[112:115], v[16:31]
	ds_read_b64_tr_b16 v[148:149], v132 offset:0x600
	ds_read_b64_tr_b16 v[150:151], v132 offset:0xe00
	s_waitcnt lgkmcnt(6)
	v_mfma_f32_32x32x16_bf16 v[16:31], v[152:155], v[120:123], v[16:31]
	ds_read_b64_tr_b16 v[152:153], v132 offset:0x1600
	ds_read_b64_tr_b16 v[154:155], v132 offset:0x1e00
	s_waitcnt lgkmcnt(6)
	v_mfma_f32_32x32x16_bf16 v[16:31], v[170:173], v[124:127], v[16:31]
	ds_read_b64_tr_b16 v[170:171], v132 offset:0x2600
	ds_read_b64_tr_b16 v[172:173], v132 offset:0x2e00
	s_waitcnt lgkmcnt(6)
	v_mfma_f32_32x32x16_bf16 v[16:31], v[188:191], v[144:147], v[16:31]
	ds_read_b64_tr_b16 v[188:189], v132 offset:0x3600
	ds_read_b64_tr_b16 v[190:191], v132 offset:0x3e00
	s_waitcnt lgkmcnt(6)
	v_mfma_f32_32x32x16_bf16 v[0:15], v[148:151], v[112:115], v[0:15]
	v_max_f32_e32 v112, v80, v81
	v_max3_f32 v112, v112, v82, v83
	v_max3_f32 v112, v112, v84, v85
	v_max3_f32 v112, v112, v86, v87
	v_max3_f32 v112, v112, v88, v89
	v_max3_f32 v112, v112, v90, v91
	v_max3_f32 v112, v112, v92, v93
	s_waitcnt lgkmcnt(4)
	v_mfma_f32_32x32x16_bf16 v[0:15], v[152:155], v[120:123], v[0:15]
	v_max3_f32 v112, v112, v94, v95
	v_max3_f32 v112, v112, v64, v65
	v_max3_f32 v112, v112, v66, v67
	v_max3_f32 v112, v112, v68, v69
	v_max3_f32 v112, v112, v70, v71
	v_max3_f32 v112, v112, v72, v73
	v_max3_f32 v112, v112, v74, v75
	v_max3_f32 v112, v112, v76, v77
	s_waitcnt lgkmcnt(2)
	v_mfma_f32_32x32x16_bf16 v[0:15], v[170:173], v[124:127], v[0:15]
	v_max3_f32 v112, v112, v78, v79
	v_mov_b32_e32 v113, v112
	s_nop 1
	v_permlane32_swap_b32_e32 v112, v113
	v_max_f32_e32 v112, v112, v113
	v_cmp_ge_f32_e32 vcc, s70, v112
	s_waitcnt lgkmcnt(0)
	v_mfma_f32_32x32x16_bf16 v[0:15], v[188:191], v[144:147], v[0:15]
	s_waitcnt vmcnt(0) lgkmcnt(0)
	s_barrier
	s_cmp_eq_u64 vcc, exec
	s_cbranch_scc1 .Lal_c_d1
	v_max_f32_e32 v242, 0, v112
	v_exp_f32_e64 v116, -v242
	s_nop 0
	v_pk_mul_f32 v[46:47], v[46:47], v[116:117] op_sel_hi:[1,0]
	v_pk_mul_f32 v[44:45], v[44:45], v[116:117] op_sel_hi:[1,0]
	v_pk_mul_f32 v[42:43], v[42:43], v[116:117] op_sel_hi:[1,0]
	v_pk_mul_f32 v[40:41], v[40:41], v[116:117] op_sel_hi:[1,0]
	v_pk_mul_f32 v[38:39], v[38:39], v[116:117] op_sel_hi:[1,0]
	v_pk_mul_f32 v[36:37], v[36:37], v[116:117] op_sel_hi:[1,0]
	v_pk_mul_f32 v[34:35], v[34:35], v[116:117] op_sel_hi:[1,0]
	v_pk_mul_f32 v[32:33], v[32:33], v[116:117] op_sel_hi:[1,0]
	v_pk_mul_f32 v[62:63], v[62:63], v[116:117] op_sel_hi:[1,0]
	v_pk_mul_f32 v[60:61], v[60:61], v[116:117] op_sel_hi:[1,0]
	v_pk_mul_f32 v[58:59], v[58:59], v[116:117] op_sel_hi:[1,0]
	v_pk_mul_f32 v[56:57], v[56:57], v[116:117] op_sel_hi:[1,0]
	v_pk_mul_f32 v[54:55], v[54:55], v[116:117] op_sel_hi:[1,0]
	v_pk_mul_f32 v[52:53], v[52:53], v[116:117] op_sel_hi:[1,0]
	v_pk_mul_f32 v[50:51], v[50:51], v[116:117] op_sel_hi:[1,0]
	v_pk_mul_f32 v[48:49], v[48:49], v[116:117] op_sel_hi:[1,0]
	v_pk_mul_f32 v[30:31], v[30:31], v[116:117] op_sel_hi:[1,0]
	v_pk_mul_f32 v[28:29], v[28:29], v[116:117] op_sel_hi:[1,0]
	v_pk_mul_f32 v[26:27], v[26:27], v[116:117] op_sel_hi:[1,0]
	v_pk_mul_f32 v[24:25], v[24:25], v[116:117] op_sel_hi:[1,0]
	v_pk_mul_f32 v[22:23], v[22:23], v[116:117] op_sel_hi:[1,0]
	v_pk_mul_f32 v[20:21], v[20:21], v[116:117] op_sel_hi:[1,0]
	v_pk_mul_f32 v[18:19], v[18:19], v[116:117] op_sel_hi:[1,0]
	v_pk_mul_f32 v[16:17], v[16:17], v[116:117] op_sel_hi:[1,0]
	v_pk_mul_f32 v[14:15], v[14:15], v[116:117] op_sel_hi:[1,0]
	v_pk_mul_f32 v[12:13], v[12:13], v[116:117] op_sel_hi:[1,0]
	v_pk_mul_f32 v[10:11], v[10:11], v[116:117] op_sel_hi:[1,0]
	v_pk_mul_f32 v[8:9], v[8:9], v[116:117] op_sel_hi:[1,0]
	v_pk_mul_f32 v[6:7], v[6:7], v[116:117] op_sel_hi:[1,0]
	v_pk_mul_f32 v[4:5], v[4:5], v[116:117] op_sel_hi:[1,0]
	v_pk_mul_f32 v[2:3], v[2:3], v[116:117] op_sel_hi:[1,0]
	v_pk_mul_f32 v[0:1], v[0:1], v[116:117] op_sel_hi:[1,0]
	v_sub_f32_e32 v80, v80, v242
	v_sub_f32_e32 v81, v81, v242
	v_sub_f32_e32 v82, v82, v242
	v_sub_f32_e32 v83, v83, v242
	v_sub_f32_e32 v84, v84, v242
	v_sub_f32_e32 v85, v85, v242
	v_sub_f32_e32 v86, v86, v242
	v_sub_f32_e32 v87, v87, v242
	v_sub_f32_e32 v88, v88, v242
	v_sub_f32_e32 v89, v89, v242
	v_sub_f32_e32 v90, v90, v242
	v_sub_f32_e32 v91, v91, v242
	v_sub_f32_e32 v92, v92, v242
	v_sub_f32_e32 v93, v93, v242
	v_sub_f32_e32 v94, v94, v242
	v_sub_f32_e32 v95, v95, v242
	v_sub_f32_e32 v64, v64, v242
	v_sub_f32_e32 v65, v65, v242
	v_sub_f32_e32 v66, v66, v242
	v_sub_f32_e32 v67, v67, v242
	v_sub_f32_e32 v68, v68, v242
	v_sub_f32_e32 v69, v69, v242
	v_sub_f32_e32 v70, v70, v242
	v_sub_f32_e32 v71, v71, v242
	v_sub_f32_e32 v72, v72, v242
	v_sub_f32_e32 v73, v73, v242
	v_sub_f32_e32 v74, v74, v242
	v_sub_f32_e32 v75, v75, v242
	v_sub_f32_e32 v76, v76, v242
	v_sub_f32_e32 v77, v77, v242
	v_sub_f32_e32 v78, v78, v242
	v_sub_f32_e32 v79, v79, v242
	v_sub_f32_e32 v226, v226, v242
	v_sub_f32_e32 v227, v227, v242
	v_sub_f32_e32 v228, v228, v242
	v_sub_f32_e32 v229, v229, v242
	v_sub_f32_e32 v230, v230, v242
	v_sub_f32_e32 v231, v231, v242
	v_sub_f32_e32 v232, v232, v242
	v_sub_f32_e32 v233, v233, v242
	v_sub_f32_e32 v234, v234, v242
	v_sub_f32_e32 v235, v235, v242
	v_sub_f32_e32 v236, v236, v242
	v_sub_f32_e32 v237, v237, v242
	v_sub_f32_e32 v238, v238, v242
	v_sub_f32_e32 v239, v239, v242
	v_sub_f32_e32 v240, v240, v242
	v_sub_f32_e32 v241, v241, v242
	s_branch .LBB0_131

; __device__ __forceinline__ void finishSM(f32x16& p0, f32x16& p1, float alpha, float& l_reg, bf16x8& pa0, bf16x8& pa1, bf16x8& pa2, bf16x8& pa3) {
; #pragma unroll
;   for (int r = 0; r < 16; ++r) p1[r] = __builtin_amdgcn_exp2f(p1[r]);
;   float ps = 0;
; #pragma unroll
;   for (int r = 0; r < 16; ++r) ps += p0[r];
; #pragma unroll
;   for (int r = 0; r < 16; ++r) ps += p1[r];
;   { auto rr = __builtin_amdgcn_permlane32_swap(__float_as_uint(ps), __float_as_uint(ps), false, false);
;     ps = __uint_as_float(rr[0]) + __uint_as_float(rr[1]); }
;   l_reg = l_reg * alpha + ps;
;     ...
;   PK4(p0, 0, pa0); PK4(p0, 8, pa1); PK4(p1, 0, pa2); PK4(p1, 8, pa3);
;     ...
; }
; template <int BUFOFF>
; __device__ __forceinline__ void qkt_diff(f32x16& p0, f32x16& p1, const int* ka, const bf16x8* qr) {
;   typedef __attribute__((address_space(3))) const bf16x8* lp;
;   p0 = f32x16{}; p1 = f32x16{};
; #pragma unroll
;   for (int d0 = 0; d0 < 4; ++d0) {
;     const int a = ka[d0] + BUFOFF;
;     const bf16x8 b0 = *(lp)(a), b1 = *(lp)(a + 8192);
;     p0 = __builtin_amdgcn_mfma_f32_32x32x16_bf16(b0, qr[d0], p0, 0, 0, 0);
;     p1 = __builtin_amdgcn_mfma_f32_32x32x16_bf16(b1, qr[d0], p1, 0, 0, 0);
;   }
; }
.LBB0_131:
	v_exp_f32_e32 v125, v64
	v_exp_f32_e32 v126, v65
	v_exp_f32_e32 v127, v66
	v_exp_f32_e32 v128, v67
	v_exp_f32_e32 v129, v68
	v_exp_f32_e32 v143, v69
	v_exp_f32_e32 v144, v70
	v_exp_f32_e32 v145, v71
	v_exp_f32_e32 v146, v72
	v_exp_f32_e32 v147, v73
	v_exp_f32_e32 v148, v74
	v_exp_f32_e32 v149, v75
	v_exp_f32_e32 v150, v76
	v_exp_f32_e32 v151, v80
	v_exp_f32_e32 v152, v81
	v_exp_f32_e32 v153, v82
	v_exp_f32_e32 v154, v83
	v_exp_f32_e32 v155, v84
	v_exp_f32_e32 v156, v85
	v_exp_f32_e32 v158, v86
	v_exp_f32_e32 v159, v87
	v_exp_f32_e32 v162, v88
	v_exp_f32_e32 v167, v89
	v_exp_f32_e32 v169, v90
	v_exp_f32_e32 v170, v91
	v_exp_f32_e32 v171, v92
	v_exp_f32_e32 v172, v93
	v_exp_f32_e32 v173, v94
	v_exp_f32_e32 v188, v95
	v_exp_f32_e32 v189, v77
	v_exp_f32_e32 v190, v78
	v_exp_f32_e32 v124, v79
	ds_read_b128 v[64:67], v138
	ds_read_b128 v[68:71], v138 offset:8192
	ds_read_b128 v[112:115], v141
	ds_read_b128 v[120:123], v141 offset:8192
	v_mov_b32_e32 v191, v125
	s_waitcnt lgkmcnt(0)
	v_mfma_f32_32x32x16_bf16 v[80:95], v[64:67], v[108:111], v[226:241]
	v_mfma_f32_32x32x16_bf16 v[64:79], v[68:71], v[108:111], v[226:241]
	v_mov_b32_e32 v192, v124
	v_mfma_f32_32x32x16_bf16 v[80:95], v[112:115], v[104:107], v[80:95]
	v_mfma_f32_32x32x16_bf16 v[64:79], v[120:123], v[104:107], v[64:79]
	ds_read_b128 v[112:115], v140
	ds_read_b128 v[120:123], v140 offset:8192
	s_waitcnt lgkmcnt(0)
	v_mfma_f32_32x32x16_bf16 v[80:95], v[112:115], v[100:103], v[80:95]
	v_mfma_f32_32x32x16_bf16 v[64:79], v[120:123], v[100:103], v[64:79]
	ds_read_b128 v[112:115], v139
	ds_read_b128 v[120:123], v139 offset:8192
	s_waitcnt lgkmcnt(0)
	v_mfma_f32_32x32x16_bf16 v[80:95], v[112:115], v[96:99], v[80:95]
	v_add_f32_e32 v112, v162, v151
	v_add_f32_e32 v243, v167, v152
	v_add_f32_e32 v244, v169, v153
	v_add_f32_e32 v245, v170, v154
	v_add_f32_e32 v246, v171, v155
	v_add_f32_e32 v247, v172, v156
	v_add_f32_e32 v251, v173, v158
	v_add_f32_e32 v252, v188, v159
	v_add_f32_e32 v112, v191, v112
	v_add_f32_e32 v243, v126, v243
	v_add_f32_e32 v244, v127, v244
	v_add_f32_e32 v245, v128, v245
	v_add_f32_e32 v246, v129, v246
	v_add_f32_e32 v247, v143, v247
	v_add_f32_e32 v251, v144, v251
	v_add_f32_e32 v252, v145, v252
	v_add_f32_e32 v112, v146, v112
	v_add_f32_e32 v243, v147, v243
	v_mfma_f32_32x32x16_bf16 v[64:79], v[120:123], v[96:99], v[64:79]
	v_add_f32_e32 v244, v148, v244
	v_add_f32_e32 v245, v149, v245
	v_add_f32_e32 v246, v150, v246
	v_add_f32_e32 v247, v189, v247
	v_add_f32_e32 v251, v190, v251
	v_add_f32_e32 v252, v192, v252
	v_add_f32_e32 v112, v112, v243
	v_add_f32_e32 v244, v244, v245
	v_add_f32_e32 v246, v246, v247
	v_add_f32_e32 v251, v251, v252
	v_add_f32_e32 v112, v112, v244
	v_add_f32_e32 v246, v246, v251
	v_add_f32_e32 v120, v112, v246
	v_mov_b32_e32 v121, v120
	v_cvt_pk_bf16_f32 v112, v151, v152
	v_cvt_pk_bf16_f32 v113, v153, v154
	v_cvt_pk_bf16_f32 v114, v155, v156
	v_cvt_pk_bf16_f32 v115, v158, v159
	s_nop 1
	v_permlane32_swap_b32_e32 v120, v121
	v_cvt_pk_bf16_f32 v122, v162, v167
	v_cvt_pk_bf16_f32 v123, v169, v170
	v_cvt_pk_bf16_f32 v124, v171, v172
	v_cvt_pk_bf16_f32 v125, v173, v188
	v_cvt_pk_bf16_f32 v126, v191, v126
	v_cvt_pk_bf16_f32 v127, v127, v128
	v_cvt_pk_bf16_f32 v128, v129, v143
	v_cvt_pk_bf16_f32 v129, v144, v145
	v_cvt_pk_bf16_f32 v144, v146, v147
	v_cvt_pk_bf16_f32 v145, v148, v149
	v_cvt_pk_bf16_f32 v146, v150, v189
	v_cvt_pk_bf16_f32 v147, v190, v192
	s_nop 0
	s_add_u32 s4, s14, 0x20000
	s_addc_u32 s5, s15, 0
	s_add_u32 s56, s14, 0x2020000
	s_mov_b32 m0, s16
	s_addc_u32 s57, s15, 0
	s_add_i32 s55, s42, s55
	s_nop 0
	global_load_lds_dwordx4 v134, s[4:5]
	s_mov_b32 m0, s17
	s_nop 0
	global_load_lds_dwordx4 v135, s[4:5]
	s_mov_b32 m0, s55
	s_nop 0
	global_load_lds_dwordx4 v136, s[56:57]
	s_add_i32 m0, s55, 0x2000
	s_nop 0
	global_load_lds_dwordx4 v137, s[56:57]
	v_lshl_add_u32 v143, s54, 14, v133
	ds_read_b64_tr_b16 v[148:149], v143 offset:0
	ds_read_b64_tr_b16 v[150:151], v143 offset:0x800
	ds_read_b64_tr_b16 v[152:153], v143 offset:0x1000
	ds_read_b64_tr_b16 v[154:155], v143 offset:0x1800
	ds_read_b64_tr_b16 v[170:171], v143 offset:0x2000
	ds_read_b64_tr_b16 v[172:173], v143 offset:0x2800
	ds_read_b64_tr_b16 v[188:189], v143 offset:0x3000
	ds_read_b64_tr_b16 v[190:191], v143 offset:0x3800
	s_nop 0
	s_waitcnt lgkmcnt(6)
	v_mfma_f32_32x32x16_bf16 v[32:47], v[148:151], v[112:115], v[32:47]
	ds_read_b64_tr_b16 v[148:149], v143 offset:0x200
	ds_read_b64_tr_b16 v[150:151], v143 offset:0xa00
	s_waitcnt lgkmcnt(6)
	v_mfma_f32_32x32x16_bf16 v[32:47], v[152:155], v[122:125], v[32:47]
	ds_read_b64_tr_b16 v[152:153], v143 offset:0x1200
	ds_read_b64_tr_b16 v[154:155], v143 offset:0x1a00
	s_waitcnt lgkmcnt(6)
	v_mfma_f32_32x32x16_bf16 v[32:47], v[170:173], v[126:129], v[32:47]
	ds_read_b64_tr_b16 v[170:171], v143 offset:0x2200
	ds_read_b64_tr_b16 v[172:173], v143 offset:0x2a00
	s_waitcnt lgkmcnt(6)
	v_mfma_f32_32x32x16_bf16 v[32:47], v[188:191], v[144:147], v[32:47]
	ds_read_b64_tr_b16 v[188:189], v143 offset:0x3200
	ds_read_b64_tr_b16 v[190:191], v143 offset:0x3a00
	s_waitcnt lgkmcnt(6)
	v_mfma_f32_32x32x16_bf16 v[48:63], v[148:151], v[112:115], v[48:63]
	ds_read_b64_tr_b16 v[148:149], v143 offset:0x400
	ds_read_b64_tr_b16 v[150:151], v143 offset:0xc00
	s_waitcnt lgkmcnt(6)
	v_mfma_f32_32x32x16_bf16 v[48:63], v[152:155], v[122:125], v[48:63]
	ds_read_b64_tr_b16 v[152:153], v143 offset:0x1400
	ds_read_b64_tr_b16 v[154:155], v143 offset:0x1c00
	s_waitcnt lgkmcnt(6)
	v_mfma_f32_32x32x16_bf16 v[48:63], v[170:173], v[126:129], v[48:63]
	ds_read_b64_tr_b16 v[170:171], v143 offset:0x2400
	ds_read_b64_tr_b16 v[172:173], v143 offset:0x2c00
	s_waitcnt lgkmcnt(6)
; #define SBAR() __builtin_amdgcn_sched_barrier(0)
; template <int MLA>
; __device__ __forceinline__ void partialSM(f32x16& p0, f32x16& p1, float& m_reg, float& mn, float& alpha) {
;     ...
;   float pmax = p0[0];
; #pragma unroll
;   for (int r = 1; r < 16; ++r) pmax = fmaxf(pmax, p0[r]);
; #pragma unroll
;   for (int r = 0; r < 16; ++r) pmax = fmaxf(pmax, p1[r]);
;   { auto rr = __builtin_amdgcn_permlane32_swap(__float_as_uint(pmax), __float_as_uint(pmax), false, false);
;     pmax = fmaxf(__uint_as_float(rr[0]), __uint_as_float(rr[1])); }
;   if (__builtin_expect(__all(pmax - m_reg <= THR / SCALE), 1)) { mn = m_reg; alpha = 1.f; }
;   else { mn = fmaxf(m_reg, pmax); alpha = __builtin_amdgcn_exp2f((m_reg - mn) * C); m_reg = mn; }
;   float mnC = -mn * C;
; #pragma unroll
;   for (int r = 0; r < 16; ++r) p0[r] = fmaf(p0[r], C, mnC);
; #pragma unroll
;   for (int r = 0; r < 16; ++r) p1[r] = fmaf(p1[r], C, mnC);
; #pragma unroll
;   for (int r = 0; r < 16; ++r) p0[r] = __builtin_amdgcn_exp2f(p0[r]);
; }
; template <int D0> __device__ __forceinline__ void pv_one_t(f32x16& od, int vb, bf16x8 pa0, bf16x8 pa1, bf16x8 pa2, bf16x8 pa3) {
;   const s16x4 l0 = tr_read<v_rd_off(D0, 0, 0)>(vb), h0 = tr_read<v_rd_off(D0, 0, 1)>(vb), l1 = tr_read<v_rd_off(D0, 1, 0)>(vb), h1 = tr_read<v_rd_off(D0, 1, 1)>(vb);
;   const s16x4 l2 = tr_read<v_rd_off(D0, 2, 0)>(vb), h2 = tr_read<v_rd_off(D0, 2, 1)>(vb), l3 = tr_read<v_rd_off(D0, 3, 0)>(vb), h3 = tr_read<v_rd_off(D0, 3, 1)>(vb);
;   asm volatile("s_waitcnt lgkmcnt(0)" ::: "memory"); SBAR();
;     ...
;   od = __builtin_amdgcn_mfma_f32_32x32x16_bf16(PK(l0, h0), pa0, od, 0, 0, 0);
;   od = __builtin_amdgcn_mfma_f32_32x32x16_bf16(PK(l1, h1), pa1, od, 0, 0, 0);
;   od = __builtin_amdgcn_mfma_f32_32x32x16_bf16(PK(l2, h2), pa2, od, 0, 0, 0);
;   od = __builtin_amdgcn_mfma_f32_32x32x16_bf16(PK(l3, h3), pa3, od, 0, 0, 0);
;     ...
; }
	v_mfma_f32_32x32x16_bf16 v[48:63], v[188:191], v[144:147], v[48:63]
	ds_read_b64_tr_b16 v[188:189], v143 offset:0x3400
	ds_read_b64_tr_b16 v[190:191], v143 offset:0x3c00
	s_waitcnt lgkmcnt(6)
	v_mfma_f32_32x32x16_bf16 v[16:31], v[148:151], v[112:115], v[16:31]
	ds_read_b64_tr_b16 v[148:149], v143 offset:0x600
	ds_read_b64_tr_b16 v[150:151], v143 offset:0xe00
	s_waitcnt lgkmcnt(6)
	v_mfma_f32_32x32x16_bf16 v[16:31], v[152:155], v[122:125], v[16:31]
	ds_read_b64_tr_b16 v[152:153], v143 offset:0x1600
	ds_read_b64_tr_b16 v[154:155], v143 offset:0x1e00
	s_waitcnt lgkmcnt(6)
	v_mfma_f32_32x32x16_bf16 v[16:31], v[170:173], v[126:129], v[16:31]
	ds_read_b64_tr_b16 v[170:171], v143 offset:0x2600
	ds_read_b64_tr_b16 v[172:173], v143 offset:0x2e00
	s_waitcnt lgkmcnt(6)
	v_mfma_f32_32x32x16_bf16 v[16:31], v[188:191], v[144:147], v[16:31]
	ds_read_b64_tr_b16 v[188:189], v143 offset:0x3600
	ds_read_b64_tr_b16 v[190:191], v143 offset:0x3e00
	s_waitcnt lgkmcnt(6)
	v_mfma_f32_32x32x16_bf16 v[0:15], v[148:151], v[112:115], v[0:15]
	v_max_f32_e32 v112, v80, v81
	v_max3_f32 v112, v112, v82, v83
	v_max3_f32 v112, v112, v84, v85
	v_max3_f32 v112, v112, v86, v87
	v_max3_f32 v112, v112, v88, v89
	v_max3_f32 v112, v112, v90, v91
	v_max3_f32 v112, v112, v92, v93
	s_waitcnt lgkmcnt(4)
	v_mfma_f32_32x32x16_bf16 v[0:15], v[152:155], v[122:125], v[0:15]
	v_max3_f32 v112, v112, v94, v95
	v_max3_f32 v112, v112, v64, v65
	v_max3_f32 v112, v112, v66, v67
	v_max3_f32 v112, v112, v68, v69
	v_max3_f32 v112, v112, v70, v71
	v_max3_f32 v112, v112, v72, v73
	v_max3_f32 v112, v112, v74, v75
	v_max3_f32 v112, v112, v76, v77
	s_waitcnt lgkmcnt(2)
	v_mfma_f32_32x32x16_bf16 v[0:15], v[170:173], v[126:129], v[0:15]
	v_max3_f32 v112, v112, v78, v79
	v_mov_b32_e32 v113, v112
	s_nop 1
	v_permlane32_swap_b32_e32 v112, v113
	v_max_f32_e32 v112, v112, v113
	v_cmp_ge_f32_e32 vcc, s70, v112
	s_waitcnt lgkmcnt(0)
	v_mfma_f32_32x32x16_bf16 v[0:15], v[188:191], v[144:147], v[0:15]
	s_waitcnt vmcnt(0) lgkmcnt(0)
	s_barrier
	s_cmp_eq_u64 vcc, exec
	s_cbranch_scc1 .Lal_c_d2
	v_max_f32_e32 v242, 0, v112
	v_exp_f32_e64 v112, -v242
	s_nop 0
	v_pk_mul_f32 v[46:47], v[46:47], v[112:113] op_sel_hi:[1,0]
	v_pk_mul_f32 v[44:45], v[44:45], v[112:113] op_sel_hi:[1,0]
	v_pk_mul_f32 v[42:43], v[42:43], v[112:113] op_sel_hi:[1,0]
	v_pk_mul_f32 v[40:41], v[40:41], v[112:113] op_sel_hi:[1,0]
	v_pk_mul_f32 v[38:39], v[38:39], v[112:113] op_sel_hi:[1,0]
	v_pk_mul_f32 v[36:37], v[36:37], v[112:113] op_sel_hi:[1,0]
	v_pk_mul_f32 v[34:35], v[34:35], v[112:113] op_sel_hi:[1,0]
	v_pk_mul_f32 v[32:33], v[32:33], v[112:113] op_sel_hi:[1,0]
	v_pk_mul_f32 v[62:63], v[62:63], v[112:113] op_sel_hi:[1,0]
	v_pk_mul_f32 v[60:61], v[60:61], v[112:113] op_sel_hi:[1,0]
	v_pk_mul_f32 v[58:59], v[58:59], v[112:113] op_sel_hi:[1,0]
	v_pk_mul_f32 v[56:57], v[56:57], v[112:113] op_sel_hi:[1,0]
	v_pk_mul_f32 v[54:55], v[54:55], v[112:113] op_sel_hi:[1,0]
	v_pk_mul_f32 v[52:53], v[52:53], v[112:113] op_sel_hi:[1,0]
	v_pk_mul_f32 v[50:51], v[50:51], v[112:113] op_sel_hi:[1,0]
	v_pk_mul_f32 v[48:49], v[48:49], v[112:113] op_sel_hi:[1,0]
	v_pk_mul_f32 v[30:31], v[30:31], v[112:113] op_sel_hi:[1,0]
	v_pk_mul_f32 v[28:29], v[28:29], v[112:113] op_sel_hi:[1,0]
	v_pk_mul_f32 v[26:27], v[26:27], v[112:113] op_sel_hi:[1,0]
	v_pk_mul_f32 v[24:25], v[24:25], v[112:113] op_sel_hi:[1,0]
	v_pk_mul_f32 v[22:23], v[22:23], v[112:113] op_sel_hi:[1,0]
	v_pk_mul_f32 v[20:21], v[20:21], v[112:113] op_sel_hi:[1,0]
	v_pk_mul_f32 v[18:19], v[18:19], v[112:113] op_sel_hi:[1,0]
	v_pk_mul_f32 v[16:17], v[16:17], v[112:113] op_sel_hi:[1,0]
	v_pk_mul_f32 v[14:15], v[14:15], v[112:113] op_sel_hi:[1,0]
	v_pk_mul_f32 v[12:13], v[12:13], v[112:113] op_sel_hi:[1,0]
	v_pk_mul_f32 v[10:11], v[10:11], v[112:113] op_sel_hi:[1,0]
	v_pk_mul_f32 v[8:9], v[8:9], v[112:113] op_sel_hi:[1,0]
	v_pk_mul_f32 v[6:7], v[6:7], v[112:113] op_sel_hi:[1,0]
	v_pk_mul_f32 v[4:5], v[4:5], v[112:113] op_sel_hi:[1,0]
	v_pk_mul_f32 v[2:3], v[2:3], v[112:113] op_sel_hi:[1,0]
	v_pk_mul_f32 v[0:1], v[0:1], v[112:113] op_sel_hi:[1,0]
	v_sub_f32_e32 v80, v80, v242
	v_sub_f32_e32 v81, v81, v242
	v_sub_f32_e32 v82, v82, v242
	v_sub_f32_e32 v83, v83, v242
	v_sub_f32_e32 v84, v84, v242
	v_sub_f32_e32 v85, v85, v242
	v_sub_f32_e32 v86, v86, v242
	v_sub_f32_e32 v87, v87, v242
	v_sub_f32_e32 v88, v88, v242
	v_sub_f32_e32 v89, v89, v242
	v_sub_f32_e32 v90, v90, v242
	v_sub_f32_e32 v91, v91, v242
	v_sub_f32_e32 v92, v92, v242
	v_sub_f32_e32 v93, v93, v242
	v_sub_f32_e32 v94, v94, v242
	v_sub_f32_e32 v95, v95, v242
	v_sub_f32_e32 v64, v64, v242
	v_sub_f32_e32 v65, v65, v242
	v_sub_f32_e32 v66, v66, v242
	v_sub_f32_e32 v67, v67, v242
	v_sub_f32_e32 v68, v68, v242
	v_sub_f32_e32 v69, v69, v242
	v_sub_f32_e32 v70, v70, v242
	v_sub_f32_e32 v71, v71, v242
	v_sub_f32_e32 v72, v72, v242
	v_sub_f32_e32 v73, v73, v242
	v_sub_f32_e32 v74, v74, v242
	v_sub_f32_e32 v75, v75, v242
	v_sub_f32_e32 v76, v76, v242
	v_sub_f32_e32 v77, v77, v242
	v_sub_f32_e32 v78, v78, v242
	v_sub_f32_e32 v79, v79, v242
	v_sub_f32_e32 v226, v226, v242
	v_sub_f32_e32 v227, v227, v242
	v_sub_f32_e32 v228, v228, v242
	v_sub_f32_e32 v229, v229, v242
	v_sub_f32_e32 v230, v230, v242
	v_sub_f32_e32 v231, v231, v242
	v_sub_f32_e32 v232, v232, v242
	v_sub_f32_e32 v233, v233, v242
	v_sub_f32_e32 v234, v234, v242
	v_sub_f32_e32 v235, v235, v242
	v_sub_f32_e32 v236, v236, v242
	v_sub_f32_e32 v237, v237, v242
	v_sub_f32_e32 v238, v238, v242
	v_sub_f32_e32 v239, v239, v242
	v_sub_f32_e32 v240, v240, v242
	v_sub_f32_e32 v241, v241, v242
	s_branch .LBB0_133
